# mixer norm f16 row path: dropped the s_waitcnt vmcnt(0) that drained the previous row's stores before issuing this row's loads (on keep_v9)
# speedup vs baseline: 1.0079x; 1.0022x over previous
.LBB0_118:
	s_and_b64 s[4:5], s[4:5], exec
	s_cselect_b32 s4, s28, s15
	s_cselect_b32 s5, s20, s14
	v_mov_b32_e32 v18, s5
	v_mov_b32_e32 v19, s4
	v_lshl_add_u64 v[18:19], v[38:39], 1, v[18:19]
	global_load_dwordx2 v[20:21], v[18:19], off
	global_load_dwordx2 v[22:23], v[18:19], off offset:512
	global_load_dwordx2 v[24:25], v[18:19], off offset:1024
	global_load_dwordx2 v[40:41], v[18:19], off offset:1536
	s_waitcnt vmcnt(3)
	v_cvt_f32_f16_e32 v30, v20
	v_cvt_f32_f16_sdwa v31, v20 dst_sel:DWORD dst_unused:UNUSED_PAD src0_sel:WORD_1
	v_cvt_f32_f16_e32 v32, v21
	v_cvt_f32_f16_sdwa v33, v21 dst_sel:DWORD dst_unused:UNUSED_PAD src0_sel:WORD_1
	s_waitcnt vmcnt(2)
	v_cvt_f32_f16_e32 v26, v22
	v_cvt_f32_f16_sdwa v27, v22 dst_sel:DWORD dst_unused:UNUSED_PAD src0_sel:WORD_1
	v_cvt_f32_f16_e32 v28, v23
	v_cvt_f32_f16_sdwa v29, v23 dst_sel:DWORD dst_unused:UNUSED_PAD src0_sel:WORD_1
	s_waitcnt vmcnt(1)
	v_cvt_f32_f16_e32 v22, v24
	v_cvt_f32_f16_sdwa v23, v24 dst_sel:DWORD dst_unused:UNUSED_PAD src0_sel:WORD_1
	v_cvt_f32_f16_e32 v24, v25
	v_cvt_f32_f16_sdwa v25, v25 dst_sel:DWORD dst_unused:UNUSED_PAD src0_sel:WORD_1
	s_waitcnt vmcnt(0)
	v_cvt_f32_f16_e32 v18, v40
	v_cvt_f32_f16_sdwa v19, v40 dst_sel:DWORD dst_unused:UNUSED_PAD src0_sel:WORD_1
	v_cvt_f32_f16_e32 v20, v41
	v_cvt_f32_f16_sdwa v21, v41 dst_sel:DWORD dst_unused:UNUSED_PAD src0_sel:WORD_1
	s_andn2_b64 vcc, exec, s[2:3]
	s_cbranch_vccnz .LBB0_113
